# attention unit head: gate LDS writes moved after the DMA issue (one exposed load latency fewer per unit)
# baseline (speedup 1.0000x reference)
; #define LAS __attribute__((address_space(3)))
; DI void attn_unit(LAS unsigned char* lds, const Args& a, int bg, int qt) {
;     const int tid = threadIdx.x, lane = tid & 63, w = __builtin_amdgcn_readfirstlane(tid >> 6);
;     const int hl = w >> 1, qs = w & 1, ql = lane & 31, hi = lane >> 5, qloc = 32 * qs + ql;
;     const int b = bg >> 1, g = bg & 1, head = g * 4 + hl;
;     const size_t tok = (size_t)b * SEQ + qt * 64 + qloc;
;     const bf16_t* Qb = (const bf16_t*)(a.ws + WS_Q); const bf16_t* KVb = (const bf16_t*)(a.ws + WS_KV);
;     const float* NG = (const float*)(a.ws + WS_NG); bf16_t* AO = (bf16_t*)(a.ws + WS_AO);
;     bf16x8 qf[4];
;     { const bf16_t* qp = Qb + tok * 512 + head * 64 + hi * 8;
; #pragma unroll
;       for (int d0 = 0; d0 < 4; ++d0) qf[d0] = *(const bf16x8*)(qp + 16 * d0); }
;     LAS float* GT = (LAS float*)(lds + LDS_GATE) + tid;
;     GT[0] = NG[tok * 24 + head]; GT[512] = NG[tok * 24 + 8 + head]; GT[1024] = NG[tok * 24 + 16 + head];
;     LAS float* IMP = (LAS float*)(lds + LDS_IMP); LAS float* VAL = (LAS float*)(lds + LDS_VAL);
;     LAS unsigned* MSK = (LAS unsigned*)(lds + LDS_MSK); LAS int* LIST = (LAS int*)(lds + LDS_LIST);
;     const unsigned lds_base = (unsigned)(uintptr_t)lds;
;     const size_t kofs = (size_t)lane * 64 + w * 8;
;     const size_t vofs = (size_t)(16 * (w & 3) + (lane >> 2)) * 64 + 32 * (w >> 2) + 8 * (lane & 3);
;     ...
;     const bf16_t* KC = (const bf16_t*)(a.ws + WS_KCC) + (size_t)bg * 8192;
;     const bf16_t* KS = KVb + 2 * KV_SLOT + (size_t)bg * SEQ * 64;
;     constexpr size_t VC_OFF = (WS_VCC - WS_KCC) / 2;
;     f32x16 oacc[2], o[2], sp[2];
; #pragma unroll
;     for (int r = 0; r < 16; ++r) { oacc[0][r] = 0.f; oacc[1][r] = 0.f; o[0][r] = 0.f; o[1][r] = 0.f; }
;     float m_ref = 0.f, l_run = 0.f;
;     const int pos = qt * 64 + qloc;
;     float mu0 = 0.f, xcross = 0.f;
;     LAS float* ip = IMP + (hl * 64 + qloc) * IMP_PITCH;
;     const bool two_cmp = qt >= 16;
;     DMA_TILE(KC, KC + VC_OFF, 0);
;     if (two_cmp) DMA_TILE(KC + 4096, KC + VC_OFF + 4096, 1);
;     DMA_TILE(KS, KS + KV_SLOT, 2);
.LBB0_739:
	s_lshr_b32 s9, s74, 2
	s_ashr_i32 s8, s74, 8
	s_and_b32 s9, s9, 56
	s_add_i32 s8, s9, s8
	s_lshr_b32 s9, s74, 6
	s_and_b32 s9, s9, 24
	s_add_i32 s9, s9, s74
	s_and_b32 s9, s9, 31
	s_and_b32 s10, s74, 0x100
	s_xor_b32 s11, s9, 31
	s_cmp_eq_u32 s10, 0
	s_cselect_b32 s73, s9, s11
	v_readfirstlane_b32 s79, v184
	s_ashr_i32 s10, s8, 1
	s_lshr_b32 s9, s79, 1
	s_ashr_i32 s11, s10, 31
	s_and_b32 s72, s9, 32
	s_lshl_b64 s[52:53], s[10:11], 11
	s_lshl_b32 s10, s73, 6
	v_or_b32_e32 v139, s72, v98
	s_lshl_b32 s9, s8, 2
	s_or_b32 s52, s52, s10
	s_lshr_b32 s28, s79, 7
	s_and_b32 s9, s9, 4
	v_or_b32_e32 v2, s52, v139
	v_mov_b32_e32 v3, s53
	s_add_i32 s29, s28, s9
	v_lshlrev_b64 v[4:5], 10, v[2:3]
	v_mov_b64_e32 v[6:7], s[38:39]
	v_lshl_add_u64 v[4:5], s[36:37], 0, v[4:5]
	s_lshl_b32 s40, s29, 7
	v_mad_u64_u32 v[2:3], s[12:13], v2, s63, v[6:7]
	v_lshl_add_u64 v[4:5], v[4:5], 0, s[40:41]
	v_mad_i32_i24 v3, s53, v235, v3
	s_lshl_b32 s40, s29, 2
	v_lshl_add_u64 v[2:3], v[2:3], 0, s[40:41]
	global_load_dword v8, v[2:3], off
	global_load_dword v9, v[2:3], off offset:32
	global_load_dword v10, v[2:3], off offset:64
	v_mov_b32_e32 v137, v101
	v_lshl_add_u64 v[2:3], v[4:5], 0, v[136:137]
	global_load_dwordx4 v[66:69], v[2:3], off
	global_load_dwordx4 v[70:73], v[2:3], off offset:32
	global_load_dwordx4 v[74:77], v[2:3], off offset:64
	global_load_dwordx4 v[78:81], v[2:3], off offset:96
	s_lshr_b32 s11, s79, 2
	s_lshr_b32 s12, s79, 3
	s_ashr_i32 s9, s8, 31
	s_lshr_b32 s40, s79, 6
	v_and_or_b32 v3, s11, 48, v147
	s_and_b32 s11, s12, 0x1fffffe0
	s_lshl_b64 s[12:13], s[8:9], 14
	v_lshl_add_u32 v2, s40, 3, v135
	v_lshl_add_u32 v3, v3, 6, s11
	s_add_u32 s12, s56, s12
	v_lshlrev_b32_e32 v100, 1, v2
	v_or_b32_e32 v2, v3, v185
	s_addc_u32 s13, s57, s13
	v_mov_b32_e32 v151, v101
	v_lshlrev_b32_e32 v150, 1, v2
	s_cmp_gt_u32 s73, 15
	v_lshl_add_u64 v[4:5], s[12:13], 0, v[100:101]
	v_lshl_add_u64 v[2:3], s[12:13], 0, v[150:151]
	s_cselect_b64 s[12:13], -1, 0
	s_cmp_lt_u32 s73, 16
	s_cselect_b64 s[16:17], -1, 0
	s_lshl_b32 s75, s40, 10
	s_add_i32 s78, s75, 0
	v_lshl_add_u64 v[6:7], v[2:3], 0, s[44:45]
	s_add_i32 s77, s78, 0x2000
	s_and_b64 vcc, exec, s[16:17]
	s_mov_b32 s11, m0
	s_mov_b32 m0, s78
	s_nop 0
	global_load_lds_dwordx4 v[4:5], off
	s_mov_b32 m0, s11
	s_nop 0
	s_mov_b32 s11, m0
	s_mov_b32 m0, s77
	s_nop 0
	global_load_lds_dwordx4 v[6:7], off
	s_mov_b32 m0, s11
	s_cbranch_vccnz .LBB0_741
	v_lshl_add_u64 v[4:5], v[4:5], 0, s[46:47]
	s_add_i32 s11, s78, 0x4000
	s_mov_b32 s18, m0
	s_mov_b32 m0, s11
	s_nop 0
	global_load_lds_dwordx4 v[4:5], off
	s_mov_b32 m0, s18
	v_lshl_add_u64 v[2:3], v[2:3], 0, s[48:49]
	s_add_i32 s11, s78, 0x6000
	s_mov_b32 s18, m0
	s_mov_b32 m0, s11
	s_nop 0
	global_load_lds_dwordx4 v[2:3], off
	s_mov_b32 m0, s18
; DI void attn_tile(LAS const unsigned char* Ks, LAS const unsigned char* VT, const bf16x8 (&qf)[4], int ql, int hi,
;                   bool need_mask, bool col_en, int lo_b, int hi_b, float& m_ref, float& l_run, f32x16 (&o)[2], f32x16 (&sp)[2]) {
;     const int lane_ = ql + 32 * hi;
;     const float bias = col_en ? -m_ref : -INFINITY;
;     const bool plain = __all(col_en && (m_ref == 0.f));
; #pragma unroll
;     for (int p = 0; p < 2; ++p) {
;         bf16x8 kf[4];
; #pragma unroll
;         for (int d0 = 0; d0 < 4; ++d0) { const int c = 2 * d0 + hi; kf[d0] = *(LAS const bf16x8*)(Ks + c * 1024 + ((ql + 32 * p) << 4)); }
;         f32x16 acc;
;         if (plain) {
; #pragma unroll
;             for (int r = 0; r < 16; ++r) acc[r] = 0.f;
; #pragma unroll
;             for (int d0 = 0; d0 < 4; ++d0) acc = MFMA32(kf[d0], qf[d0], acc);
;         } else {
; #pragma unroll
;             for (int r = 0; r < 16; ++r) acc[r] = bias;
; #pragma unroll
;             for (int d0 = 0; d0 < 4; ++d0) acc = MFMA32(kf[d0], qf[d0], acc);
;         }
;         sp[p] = acc;
;     }
;     if (need_mask) {
; #pragma unroll
;         for (int p = 0; p < 2; ++p)
; #pragma unroll
;             for (int r = 0; r < 16; ++r) { const int kvl = 32 * p + (r & 3) + 8 * (r >> 2) + 4 * hi; const bool ok = (kvl <= hi_b) && (kvl > lo_b); sp[p][r] = ok ? sp[p][r] : -INFINITY; }
;     }
;     float tm = fmaxf(fmaxf(sp[0][0], sp[0][1]), sp[1][0]);
; #pragma unroll
;     for (int r = 2; r < 16; r += 2) tm = fmaxf(fmaxf(tm, sp[0][r]), sp[0][r + 1]);
; #pragma unroll
;     for (int r = 1; r < 15; r += 2) tm = fmaxf(fmaxf(tm, sp[1][r]), sp[1][r + 1]);
;     tm = fmaxf(tm, sp[1][15]);
;     tm = half_max(tm);
;     if (__any((tm > 16.f) || ((tm < -16.f) && (tm > -INFINITY)))) {
;         const bool up = tm > 16.f;
;         const bool dn = (tm < -16.f) && (tm > -INFINITY) && (half_sum(l_run) == 0.f);
; DI void attn_unit(LAS unsigned char* lds, const Args& a, int bg, int qt) {
;     ...
;     DMA_TILE(KS, KS + KV_SLOT, 2);
;     WAIT_VM(0);
;     __syncthreads();
; #pragma unroll
;     for (int ct = 0; ct < 2; ++ct) {
;         if (ct == 0 || two_cmp) {
;             const int hb = ((pos - 31) >> 4) - 64 * ct;
;             LAS const unsigned char* kb = lds + ct * ATT_BUF;
;             attn_tile(kb, kb + LDS_VT, qf, ql, hi, true, true, -1, hb, m_ref, l_run, o, sp);
.LBB0_741:
	s_lshl_b64 s[8:9], s[8:9], 18
	s_add_u32 s54, s58, s8
	s_addc_u32 s55, s59, s9
	v_lshl_add_u64 v[2:3], s[54:55], 0, v[100:101]
	s_add_i32 s8, s78, 0x8000
	s_mov_b32 s9, m0
	s_mov_b32 m0, s8
	s_nop 0
	global_load_lds_dwordx4 v[2:3], off
	s_mov_b32 m0, s9
	v_lshl_add_u64 v[2:3], s[54:55], 0, v[150:151]
	v_lshl_add_u64 v[2:3], v[2:3], 0, s[50:51]
	s_add_i32 s8, s78, 0xa000
	s_mov_b32 s9, m0
	s_mov_b32 m0, s8
	s_nop 0
	global_load_lds_dwordx4 v[2:3], off
	s_mov_b32 m0, s9
	s_waitcnt vmcnt(0)
	ds_write2st64_b32 v133, v8, v9 offset1:8
	ds_write_b32 v133, v10 offset:4096
	s_waitcnt lgkmcnt(0)
	s_barrier
	ds_read_b128 v[2:5], v236
	ds_read_b128 v[6:9], v236 offset:512
	s_waitcnt vmcnt(3) lgkmcnt(1)
	v_mfma_f32_32x32x16_bf16 v[18:33], v[2:5], v[66:69], 0
	ds_read_b128 v[34:37], v236 offset:2048
	ds_read_b128 v[38:41], v236 offset:2560
	s_sub_i32 s8, s10, 31
	s_waitcnt vmcnt(2) lgkmcnt(1)
	v_mfma_f32_32x32x16_bf16 v[18:33], v[34:37], v[70:73], v[18:33]
	ds_read_b128 v[34:37], v236 offset:4096
	ds_read_b128 v[44:47], v236 offset:4608
	v_mfma_f32_32x32x16_bf16 v[2:17], v[6:9], v[66:69], 0
	s_waitcnt vmcnt(1) lgkmcnt(1)
	v_mfma_f32_32x32x16_bf16 v[18:33], v[34:37], v[74:77], v[18:33]
	ds_read_b128 v[34:37], v236 offset:6144
	ds_read_b128 v[48:51], v236 offset:6656
	s_waitcnt vmcnt(0) lgkmcnt(1)
	v_mfma_f32_32x32x16_bf16 v[18:33], v[34:37], v[78:81], v[18:33]
	v_add_u32_e32 v34, s8, v139
	v_ashrrev_i32_e32 v151, 4, v34
	v_cmp_le_i32_e32 vcc, v1, v151
	v_mfma_f32_32x32x16_bf16 v[2:17], v[38:41], v[70:73], v[2:17]
	s_nop 7
	v_cndmask_b32_e32 v43, v237, v18, vcc
	v_cmp_gt_i32_e32 vcc, v151, v1
	s_nop 1
	v_cndmask_b32_e32 v42, v237, v19, vcc
	v_cmp_le_i32_e32 vcc, v99, v151
	v_mfma_f32_32x32x16_bf16 v[2:17], v[44:47], v[74:77], v[2:17]
	s_nop 0
	v_cndmask_b32_e32 v41, v237, v21, vcc
	v_cmp_le_i32_e32 vcc, v104, v151
	s_nop 1
	v_cndmask_b32_e32 v40, v237, v20, vcc
	v_cmp_le_i32_e32 vcc, v103, v151
	s_waitcnt lgkmcnt(0)
	v_mfma_f32_32x32x16_bf16 v[2:17], v[48:51], v[78:81], v[2:17]
	v_cndmask_b32_e32 v39, v237, v23, vcc
	v_cmp_le_i32_e32 vcc, v106, v151
	s_nop 1
	v_cndmask_b32_e32 v38, v237, v22, vcc
	v_cmp_le_i32_e32 vcc, v105, v151
	s_nop 1
	v_cndmask_b32_e32 v37, v237, v25, vcc
	v_cmp_le_i32_e32 vcc, v108, v151
	s_nop 1
	v_cndmask_b32_e32 v36, v237, v24, vcc
	v_cmp_le_i32_e32 vcc, v107, v151
	s_nop 1
	v_cndmask_b32_e32 v25, v237, v27, vcc
	v_cmp_le_i32_e32 vcc, v110, v151
	s_nop 1
	v_cndmask_b32_e32 v24, v237, v26, vcc
	v_cmp_le_i32_e32 vcc, v109, v151
	s_nop 1
	v_cndmask_b32_e32 v23, v237, v29, vcc
	v_cmp_le_i32_e32 vcc, v112, v151
	s_nop 1
	v_cndmask_b32_e32 v22, v237, v28, vcc
	v_cmp_le_i32_e32 vcc, v111, v151
	s_nop 1
	v_cndmask_b32_e32 v21, v237, v31, vcc
	v_cmp_le_i32_e32 vcc, v114, v151
	s_nop 1
	v_cndmask_b32_e32 v20, v237, v30, vcc
	v_cmp_le_i32_e32 vcc, v113, v151
	s_nop 1
	v_cndmask_b32_e32 v19, v237, v33, vcc
	v_cmp_le_i32_e32 vcc, v116, v151
	s_nop 1
	v_cndmask_b32_e32 v18, v237, v32, vcc
	v_cmp_le_i32_e32 vcc, v115, v151
	s_nop 1
	v_cndmask_b32_e32 v31, v237, v3, vcc
	v_cmp_le_i32_e32 vcc, v118, v151
	s_nop 1
	v_cndmask_b32_e32 v35, v237, v2, vcc
	v_cmp_le_i32_e32 vcc, v117, v151
	s_nop 1
	v_cndmask_b32_e32 v30, v237, v5, vcc
	v_cmp_le_i32_e32 vcc, v120, v151
	s_nop 1
	v_cndmask_b32_e32 v33, v237, v4, vcc
	v_cmp_le_i32_e32 vcc, v119, v151
	s_nop 1
	v_cndmask_b32_e32 v5, v237, v7, vcc
	v_cmp_le_i32_e32 vcc, v122, v151
	s_nop 1
	v_cndmask_b32_e32 v32, v237, v6, vcc
	v_cmp_le_i32_e32 vcc, v121, v151
	s_nop 1
	v_cndmask_b32_e32 v4, v237, v9, vcc
	v_cmp_le_i32_e32 vcc, v124, v151
	v_max_f32_e32 v9, v42, v42
	s_nop 0
	v_cndmask_b32_e32 v8, v237, v8, vcc
	v_cmp_le_i32_e32 vcc, v123, v151
	s_nop 1
	v_cndmask_b32_e32 v3, v237, v11, vcc
	v_cmp_le_i32_e32 vcc, v126, v151
	s_nop 1
	v_cndmask_b32_e32 v7, v237, v10, vcc
	v_max_f32_e32 v10, v43, v43
	v_max_f32_e32 v9, v10, v9
	v_max3_f32 v9, v9, v35, v40
	v_max3_f32 v9, v9, v41, v38
	v_max3_f32 v9, v9, v39, v36
	v_max3_f32 v9, v9, v37, v24
	v_max3_f32 v9, v9, v25, v22
	v_max3_f32 v9, v9, v23, v20
	v_max3_f32 v9, v9, v21, v18
	v_cmp_le_i32_e32 vcc, v125, v151
	v_max3_f32 v9, v9, v19, v31
	v_max3_f32 v9, v9, v33, v30
	v_cndmask_b32_e32 v2, v237, v13, vcc
	v_cmp_le_i32_e32 vcc, v128, v151
	v_max3_f32 v9, v9, v32, v5
	v_max3_f32 v9, v9, v8, v4
	v_cndmask_b32_e32 v6, v237, v12, vcc
	v_cmp_le_i32_e32 vcc, v127, v151
	v_max3_f32 v9, v9, v7, v3
	v_max3_f32 v9, v9, v6, v2
	v_cndmask_b32_e32 v26, v237, v15, vcc
	v_cmp_le_i32_e32 vcc, v130, v151
	s_nop 1
	v_cndmask_b32_e32 v29, v237, v14, vcc
	v_cmp_le_i32_e32 vcc, v129, v151
	v_max3_f32 v9, v9, v29, v26
	s_nop 0
	v_cndmask_b32_e32 v27, v237, v17, vcc
	v_cmp_le_i32_e32 vcc, v132, v151
	s_nop 1
	v_cndmask_b32_e32 v28, v237, v16, vcc
	v_max3_f32 v9, v9, v28, v27
	v_mov_b32_e32 v10, v9
	s_nop 1
	v_permlane32_swap_b32_e32 v9, v10
	v_max_f32_e32 v10, v10, v10
	v_max_f32_e32 v9, v9, v9
	v_max_f32_e32 v9, v9, v10
	v_cmp_gt_f32_e32 vcc, s66, v9
	v_cmp_lg_f32_e64 s[10:11], s64, v9
	v_cmp_lt_f32_e64 s[8:9], s65, v9
	s_and_b64 s[20:21], vcc, s[10:11]
	s_or_b64 vcc, s[8:9], s[20:21]
	s_cbranch_vccz .LBB0_745
	s_mov_b64 s[10:11], 0
	s_and_saveexec_b64 s[18:19], s[20:21]
	v_mov_b32_e32 v10, v101
	v_mov_b32_e32 v11, v101
	s_nop 1
	v_permlane32_swap_b32_e32 v10, v11
	v_add_f32_e32 v10, v10, v11
	v_cmp_eq_f32_e32 vcc, 0, v10
	s_and_b64 s[10:11], vcc, exec
	s_or_b64 exec, exec, s[18:19]
	s_or_b64 vcc, s[8:9], s[10:11]
	v_cndmask_b32_e32 v10, 0, v9, vcc
	v_exp_f32_e64 v9, -v10
	v_add_f32_e32 v137, 0, v10
	v_pk_add_f32 v[42:43], v[42:43], v[10:11] op_sel_hi:[1,0] neg_lo:[0,1] neg_hi:[0,1]
	v_pk_add_f32 v[40:41], v[40:41], v[10:11] op_sel_hi:[1,0] neg_lo:[0,1] neg_hi:[0,1]
	v_mul_f32_e32 v9, 0, v9
	v_cndmask_b32_e64 v34, 0, v9, s[8:9]
	v_pk_add_f32 v[38:39], v[38:39], v[10:11] op_sel_hi:[1,0] neg_lo:[0,1] neg_hi:[0,1]
	v_pk_add_f32 v[36:37], v[36:37], v[10:11] op_sel_hi:[1,0] neg_lo:[0,1] neg_hi:[0,1]
	v_pk_add_f32 v[24:25], v[24:25], v[10:11] op_sel_hi:[1,0] neg_lo:[0,1] neg_hi:[0,1]
	v_pk_add_f32 v[22:23], v[22:23], v[10:11] op_sel_hi:[1,0] neg_lo:[0,1] neg_hi:[0,1]
	v_pk_add_f32 v[20:21], v[20:21], v[10:11] op_sel_hi:[1,0] neg_lo:[0,1] neg_hi:[0,1]
	v_pk_add_f32 v[18:19], v[18:19], v[10:11] op_sel_hi:[1,0] neg_lo:[0,1] neg_hi:[0,1]
	v_sub_f32_e32 v35, v35, v10
	v_sub_f32_e32 v31, v31, v10
	v_sub_f32_e32 v33, v33, v10
	v_sub_f32_e32 v30, v30, v10
	v_sub_f32_e32 v32, v32, v10
	v_sub_f32_e32 v5, v5, v10
	v_sub_f32_e32 v8, v8, v10
	v_sub_f32_e32 v4, v4, v10
	v_sub_f32_e32 v7, v7, v10
	v_sub_f32_e32 v3, v3, v10
	v_sub_f32_e32 v6, v6, v10
	v_sub_f32_e32 v2, v2, v10
	v_sub_f32_e32 v29, v29, v10
	v_sub_f32_e32 v26, v26, v10
	v_sub_f32_e32 v28, v28, v10
	v_sub_f32_e32 v27, v27, v10
	s_branch .LBB0_746
